# grid barrier: non-leader WGs poll the cross-XCC release generation directly (one hop less)
# baseline (speedup 1.0000x reference)
.LBB0_41:
	s_or_b64 exec, exec, s[6:7]
	v_cvt_f32_u32_e32 v6, v4
	s_waitcnt vmcnt(0)
	v_readfirstlane_b32 s6, v5
	v_sub_u32_e32 v5, 0, v4
	v_rcp_iflag_f32_e32 v6, v6
	v_add_u32_e32 v7, s6, v2
	v_mul_f32_e32 v6, 0x4f7ffffe, v6
	v_cvt_u32_f32_e32 v6, v6
	v_mul_lo_u32 v2, v5, v6
	v_mul_hi_u32 v2, v6, v2
	v_add_u32_e32 v2, v6, v2
	v_mul_hi_u32 v2, v7, v2
	v_mul_lo_u32 v5, v2, v4
	v_sub_u32_e32 v5, v7, v5
	v_add_u32_e32 v6, 1, v2
	v_sub_u32_e32 v8, v5, v4
	v_cmp_ge_u32_e32 vcc, v5, v4
	s_nop 1
	v_cndmask_b32_e32 v2, v2, v6, vcc
	v_cndmask_b32_e32 v5, v5, v8, vcc
	v_add_u32_e32 v6, 1, v2
	v_cmp_ge_u32_e32 vcc, v5, v4
	v_add_u32_e32 v5, 1, v7
	s_nop 0
	v_cndmask_b32_e32 v2, v2, v6, vcc
	v_mul_lo_u32 v6, v4, v2
	v_add_u32_e32 v4, v6, v4
	v_cmp_ne_u32_e32 vcc, v5, v4
	s_and_saveexec_b64 s[6:7], vcc
	s_xor_b64 s[6:7], exec, s[6:7]
	s_cbranch_execz .LBB0_55
	s_waitcnt lgkmcnt(0)
	global_load_dword v1, v3, s[76:77] sc1
	s_waitcnt vmcnt(0)
	v_cmp_eq_u32_e32 vcc, v1, v2
	s_and_saveexec_b64 s[12:13], vcc
	s_cbranch_execz .LBB0_54
	s_mov_b32 s24, 1
	s_mov_b64 s[14:15], 0
	s_branch .LBB0_45

.LBB0_47:
	s_add_i32 s24, s24, 1
	s_mov_b64 s[20:21], -1
	global_load_dword v1, v3, s[76:77] sc1
	s_waitcnt vmcnt(0)
	v_cmp_ne_u32_e32 vcc, v1, v2
	s_orn2_b64 s[18:19], vcc, exec
	s_branch .LBB0_44

.LBB0_72:
	s_or_b64 exec, exec, s[6:7]
	s_mov_b64 s[6:7], exec
	v_mbcnt_lo_u32_b32 v1, s6, 0
	v_mbcnt_hi_u32_b32 v1, s7, v1
	v_cmp_eq_u32_e32 vcc, 0, v1
	s_waitcnt vmcnt(0)
	buffer_inv sc1
	s_and_saveexec_b64 s[12:13], vcc
	s_cbranch_execz .LBB0_74
	s_nop 0
